# PLE projection GEMM moved from P1 tail to P3b; 31360 conversion items (28/wave: w_down + gate_up tail) deferred from P0 into P1 tail
# speedup vs baseline: 1.0010x; 1.0010x over previous
.LBB0_9:
	s_cmp_lg_u32 s101, 0
	s_cbranch_scc1 .Lcv_go
	s_cmp_lt_i32 s80, 0x13000
	s_cbranch_scc1 .Lcv_go
	s_cmp_lt_i32 s80, 0x1aa80
	s_cbranch_scc1 .LBB0_8

.LBB0_399:
	s_cmpk_eq_i32 s88, 0x100
	s_cselect_b64 s[0:1], -1, 0
	s_cmpk_lg_i32 s88, 0x100
	v_writelane_b32 v250, s0, 23
	s_cselect_b64 s[22:23], -1, 0
	s_cmpk_lt_i32 s2, 0x74
	v_writelane_b32 v250, s1, 24
	s_cselect_b64 s[0:1], -1, 0
	s_or_b64 s[0:1], s[0:1], s[22:23]
	s_and_b64 vcc, exec, s[0:1]
	s_cbranch_vccnz .LBB0_416
	v_writelane_b32 v248, s0, 0
	v_writelane_b32 v248, s1, 1
	v_writelane_b32 v248, s2, 2
	v_writelane_b32 v248, s3, 3
	v_writelane_b32 v248, s4, 4
	v_writelane_b32 v248, s5, 5
	v_writelane_b32 v248, s6, 6
	v_writelane_b32 v248, s7, 7
	v_writelane_b32 v248, s8, 8
	v_writelane_b32 v248, s9, 9
	v_writelane_b32 v248, s10, 10
	v_writelane_b32 v248, s11, 11
	v_writelane_b32 v248, s12, 12
	v_writelane_b32 v248, s13, 13
	v_writelane_b32 v248, s14, 14
	v_writelane_b32 v248, s15, 15
	v_writelane_b32 v248, s16, 16
	v_writelane_b32 v248, s17, 17
	v_writelane_b32 v248, s18, 18
	v_writelane_b32 v248, s19, 19
	v_writelane_b32 v248, s20, 20
	v_writelane_b32 v248, s21, 21
	v_writelane_b32 v248, s22, 22
	v_writelane_b32 v248, s23, 23
	v_writelane_b32 v248, s24, 24
	v_writelane_b32 v248, s25, 25
	v_writelane_b32 v248, s26, 26
	v_writelane_b32 v248, s27, 27
	v_writelane_b32 v248, s28, 28
	v_writelane_b32 v248, s29, 29
	v_writelane_b32 v248, s30, 30
	v_writelane_b32 v248, s31, 31
	v_writelane_b32 v248, s32, 32
	v_writelane_b32 v248, s33, 33
	v_writelane_b32 v248, s34, 34
	v_writelane_b32 v248, s35, 35
	v_writelane_b32 v248, s36, 36
	v_writelane_b32 v248, s37, 37
	v_writelane_b32 v248, s38, 38
	v_writelane_b32 v248, s39, 39
	v_writelane_b32 v248, s40, 40
	v_writelane_b32 v248, s41, 41
	v_writelane_b32 v248, s42, 42
	v_writelane_b32 v248, s43, 43
	v_writelane_b32 v248, s44, 44
	v_writelane_b32 v248, s45, 45
	v_writelane_b32 v248, s46, 46
	v_writelane_b32 v248, s47, 47
	v_writelane_b32 v248, s48, 48
	v_writelane_b32 v248, s49, 49
	v_writelane_b32 v248, s50, 50
	v_writelane_b32 v248, s51, 51
	v_writelane_b32 v248, s52, 52
	v_writelane_b32 v248, s53, 53
	v_writelane_b32 v248, s54, 54
	v_writelane_b32 v248, s55, 55
	v_writelane_b32 v248, s56, 56
	v_writelane_b32 v248, s57, 57
	v_writelane_b32 v248, s58, 58
	v_writelane_b32 v248, s59, 59
	v_writelane_b32 v248, s60, 60
	v_writelane_b32 v248, s61, 61
	v_writelane_b32 v248, s62, 62
	v_writelane_b32 v248, s63, 63
	v_writelane_b32 v249, s64, 0
	v_writelane_b32 v249, s65, 1
	v_writelane_b32 v249, s66, 2
	v_writelane_b32 v249, s67, 3
	v_writelane_b32 v249, s68, 4
	v_writelane_b32 v249, s69, 5
	v_writelane_b32 v249, s70, 6
	v_writelane_b32 v249, s71, 7
	v_writelane_b32 v249, s72, 8
	v_writelane_b32 v249, s73, 9
	v_writelane_b32 v249, s74, 10
	v_writelane_b32 v249, s75, 11
	v_writelane_b32 v249, s76, 12
	v_writelane_b32 v249, s77, 13
	v_writelane_b32 v249, s78, 14
	v_writelane_b32 v249, s79, 15
	v_writelane_b32 v249, s80, 16
	v_writelane_b32 v249, s81, 17
	v_writelane_b32 v249, s82, 18
	v_writelane_b32 v249, s83, 19
	v_writelane_b32 v249, s84, 20
	v_writelane_b32 v249, s85, 21
	v_writelane_b32 v249, s86, 22
	v_writelane_b32 v249, s87, 23
	v_writelane_b32 v249, s88, 24
	v_writelane_b32 v249, s89, 25
	v_writelane_b32 v249, s90, 26
	v_writelane_b32 v249, s91, 27
	v_writelane_b32 v249, s92, 28
	v_writelane_b32 v249, s93, 29
	v_writelane_b32 v249, s94, 30
	v_writelane_b32 v249, s95, 31
	v_writelane_b32 v249, s96, 32
	v_writelane_b32 v249, s97, 33
	v_readlane_b32 s1, v250, 9
	v_readlane_b32 s86, v250, 10
	v_readlane_b32 s87, v250, 11
	s_sub_i32 s0, s2, 0x74
	s_lshl_b32 s0, s0, 3
	s_nop 1
	s_add_i32 s12, s0, s1
	s_add_i32 s12, s12, 0x13000
	s_movk_i32 s14, 0x460
	s_mov_b32 s100, 0x1aa80
	s_mov_b32 s101, 1
	s_branch .Lcv_entry

.LBB0_961:
	s_cmpk_gt_i32 s66, 0x29f
	v_mbcnt_lo_u32_b32 v8, -1, 0
	v_mbcnt_hi_u32_b32 v8, -1, v8
	s_nop 0
	s_cbranch_scc1 .LBB0_978
	v_lshl_add_u32 v0, v8, 4, s93
	v_add_u32_e32 v1, 0x2000, v0
	v_ashrrev_i32_e32 v2, 31, v1
	v_lshrrev_b32_e32 v2, 22, v2
	v_add_u32_e32 v2, v1, v2
	v_ashrrev_i32_e32 v2, 10, v2
	v_mul_i32_i24_e32 v3, 0x400, v2
	v_sub_u32_e32 v1, v1, v3
	v_lshrrev_b32_e32 v3, 4, v1
	v_bitop3_b32 v1, v3, v1, 32 bitop3:0x6c
	v_ashrrev_i32_e32 v3, 31, v1
	v_lshrrev_b32_e32 v3, 26, v3
	v_add_u32_e32 v3, v1, v3
	v_ashrrev_i32_e32 v4, 6, v3
	v_and_b32_e32 v3, 0xffc0, v3
	v_sub_u32_e32 v1, v1, v3
	v_lshlrev_b32_e32 v5, 3, v2
	v_lshrrev_b16_e32 v3, 7, v1
	v_and_b32_e32 v5, -16, v5
	v_and_b32_e32 v3, 1, v3
	v_add_u32_e32 v5, v4, v5
	v_add_u16_e32 v1, v1, v3
	v_mov_b32_e32 v3, 1
	v_and_b32_e32 v4, 3, v4
	s_mov_b32 s10, 0x7fffe0
	v_lshrrev_b32_e32 v6, 2, v5
	v_lshlrev_b32_e32 v7, 1, v5
	v_lshlrev_b32_e32 v2, 5, v2
	v_ashrrev_i16_sdwa v1, v3, sext(v1) dst_sel:DWORD dst_unused:UNUSED_PAD src0_sel:DWORD src1_sel:BYTE_0
	v_and_or_b32 v4, v5, s10, v4
	v_and_b32_e32 v6, 4, v6
	v_and_b32_e32 v7, 24, v7
	v_and_b32_e32 v2, 32, v2
	v_bfe_i32 v1, v1, 0, 16
	v_or3_b32 v4, v4, v6, v7
	v_add_lshl_u32 v1, v2, v1, 1
	s_load_dwordx2 s[0:1], s[64:65], 0xc0
	v_lshl_add_u32 v128, v4, 9, v1
	v_lshl_add_u32 v130, v5, 9, v1
	v_ashrrev_i32_e32 v1, 31, v0
	v_lshrrev_b32_e32 v1, 22, v1
	v_add_u32_e32 v1, v0, v1
	v_ashrrev_i32_e32 v1, 10, v1
	s_ashr_i32 s36, s7, 31
	s_ashr_i32 s37, s40, 31
	v_mul_i32_i24_e32 v2, 0x400, v1
	s_waitcnt lgkmcnt(0)
	s_add_u32 s38, s0, 0x1f800000
	v_sub_u32_e32 v0, v0, v2
	s_addc_u32 s39, s1, 0
	v_lshrrev_b32_e32 v2, 4, v0
	s_add_u32 s41, s0, 0x1f500000
	v_bitop3_b32 v0, v2, v0, 32 bitop3:0x6c
	s_addc_u32 s42, s1, 0
	s_lshr_b32 s8, s37, 29
	v_ashrrev_i32_e32 v2, 31, v0
	s_add_i32 s8, s40, s8
	v_lshrrev_b32_e32 v2, 26, v2
	s_ashr_i32 s9, s8, 3
	s_and_b32 s8, s8, -8
	v_add_u32_e32 v2, v0, v2
	v_lshlrev_b32_e32 v5, 3, v1
	s_sub_i32 s8, s40, s8
	v_ashrrev_i32_e32 v4, 6, v2
	v_and_b32_e32 v5, -16, v5
	s_cmp_lt_i32 s8, 0
	v_add_u32_e32 v5, v4, v5
	v_and_b32_e32 v4, 3, v4
	s_movk_i32 s43, 0x49
	v_and_or_b32 v4, v5, s10, v4
	s_cselect_b32 s10, s43, 0x48
	s_mul_i32 s8, s8, s10
	s_add_i32 s8, s8, s9
	s_ashr_i32 s9, s8, 31
	s_lshr_b32 s9, s9, 25
	s_add_i32 s9, s8, s9
	s_ashr_i32 s10, s9, 7
	v_and_b32_e32 v2, 0xc0, v2
	s_lshl_b32 s10, s10, 3
	v_sub_u32_e32 v0, v0, v2
	s_sub_i32 s11, 36, s10
	v_lshlrev_b32_e32 v1, 5, v1
	v_ashrrev_i16_sdwa v0, v3, sext(v0) dst_sel:DWORD dst_unused:UNUSED_PAD src0_sel:DWORD src1_sel:BYTE_0
	s_min_u32 s11, s11, 8
	s_and_b32 s9, s9, 0xffffff80
	v_and_b32_e32 v1, 32, v1
	v_bfe_i32 v0, v0, 0, 16
	s_sub_i32 s15, s8, s9
	v_cvt_f32_ubyte0_e32 v2, s11
	v_add_lshl_u32 v0, v1, v0, 1
	v_cvt_f32_i32_e32 v1, s15
	v_rcp_iflag_f32_e32 v3, v2
	v_lshrrev_b32_e32 v6, 2, v5
	v_lshlrev_b32_e32 v7, 1, v5
	v_and_b32_e32 v6, 4, v6
	v_and_b32_e32 v7, 24, v7
	v_or3_b32 v4, v4, v6, v7
	v_lshl_add_u32 v132, v4, 9, v0
	v_lshl_add_u32 v134, v5, 9, v0
	v_mul_f32_e32 v0, v1, v3
	v_trunc_f32_e32 v0, v0
	v_fma_f32 v1, -v0, v2, v1
	v_cvt_i32_f32_e32 v0, v0
	s_ashr_i32 s8, s15, 30
	s_or_b32 s14, s8, 1
	v_cmp_ge_f32_e64 s[8:9], |v1|, v2
	s_and_b64 s[8:9], s[8:9], exec
	s_cselect_b32 s8, s14, 0
	v_readfirstlane_b32 s9, v0
	s_add_i32 s14, s9, s8
	s_mul_i32 s8, s14, s11
	s_sub_i32 s8, s15, s8
	s_sext_i32_i8 s8, s8
	s_add_i32 s24, s10, s8
	s_ashr_i32 s25, s24, 31
	s_bfe_i64 s[10:11], s[14:15], 0x80000
	s_lshl_b64 s[8:9], s[24:25], 17
	s_lshl_b64 s[10:11], s[10:11], 17
	s_add_u32 s26, s41, s10
	s_addc_u32 s27, s42, s11
	s_add_i32 s25, s93, 0
	s_add_i32 m0, s25, 0x10000
	v_mov_b32_e32 v133, 0
	global_load_lds_dwordx4 v132, s[26:27]
	s_add_i32 m0, s25, 0x12000
	s_add_u32 s28, s38, s8
	s_addc_u32 s29, s39, s9
	s_add_u32 s8, s26, 0x10000
	global_load_lds_dwordx4 v128, s[26:27]
	s_addc_u32 s9, s27, 0
	s_add_i32 m0, s25, 0x14000
	s_add_i32 s44, s25, 0x2000
	global_load_lds_dwordx4 v132, s[8:9]
	s_add_i32 m0, s25, 0x16000
	v_readlane_b32 s4, v250, 21
	global_load_lds_dwordx4 v128, s[8:9]
	s_mov_b32 m0, s25
	s_add_u32 s8, s28, 0x10000
	global_load_lds_dwordx4 v134, s[28:29]
	s_mov_b32 m0, s44
	s_addc_u32 s9, s29, 0
	s_add_i32 s45, s25, 0x4000
	global_load_lds_dwordx4 v130, s[28:29]
	s_mov_b32 m0, s45
	s_add_i32 s46, s25, 0x6000
	global_load_lds_dwordx4 v134, s[8:9]
	s_mov_b32 m0, s46
	v_mov_b32_e32 v129, v133
	global_load_lds_dwordx4 v130, s[8:9]
	v_mov_b32_e32 v135, v133
	v_mov_b32_e32 v131, v133
	v_readlane_b32 s5, v250, 22
	s_mov_b32 s47, 0
	v_lshl_add_u64 v[6:7], s[26:27], 0, v[132:133]
	v_lshl_add_u64 v[4:5], s[26:27], 0, v[128:129]
	v_lshl_add_u64 v[0:1], s[28:29], 0, v[134:135]
	s_and_b64 vcc, exec, s[4:5]
	v_lshl_add_u64 v[2:3], s[28:29], 0, v[130:131]
	s_cbranch_vccnz .LBB0_965
	s_barrier
